# P12 final norm: row-sum butterflies via DPP adds and v_permlane16/32_swap instead of ds_bpermute
# baseline (speedup 1.0000x reference)
.Lp12_nonext:
	v_mul_f32_e32 v80, v48, v48
	v_mul_f32_e32 v82, v64, v64
	v_mul_f32_e32 v81, v49, v49
	v_mul_f32_e32 v83, v65, v65
	v_fmac_f32_e32 v80, v50, v50
	v_fmac_f32_e32 v82, v66, v66
	v_fmac_f32_e32 v81, v51, v51
	v_fmac_f32_e32 v83, v67, v67
	v_fmac_f32_e32 v80, v52, v52
	v_fmac_f32_e32 v82, v68, v68
	v_fmac_f32_e32 v81, v53, v53
	v_fmac_f32_e32 v83, v69, v69
	v_fmac_f32_e32 v80, v54, v54
	v_fmac_f32_e32 v82, v70, v70
	v_fmac_f32_e32 v81, v55, v55
	v_fmac_f32_e32 v83, v71, v71
	v_fmac_f32_e32 v80, v56, v56
	v_fmac_f32_e32 v82, v72, v72
	v_fmac_f32_e32 v81, v57, v57
	v_fmac_f32_e32 v83, v73, v73
	v_fmac_f32_e32 v80, v58, v58
	v_fmac_f32_e32 v82, v74, v74
	v_fmac_f32_e32 v81, v59, v59
	v_fmac_f32_e32 v83, v75, v75
	v_fmac_f32_e32 v80, v60, v60
	v_fmac_f32_e32 v82, v76, v76
	v_fmac_f32_e32 v81, v61, v61
	v_fmac_f32_e32 v83, v77, v77
	v_fmac_f32_e32 v80, v62, v62
	v_fmac_f32_e32 v82, v78, v78
	v_fmac_f32_e32 v81, v63, v63
	v_fmac_f32_e32 v83, v79, v79
	v_add_f32_e32 v80, v80, v81
	v_add_f32_e32 v82, v82, v83
	s_nop 1
	v_add_f32_dpp v80, v80, v80 quad_perm:[1,0,3,2] row_mask:0xf bank_mask:0xf
	s_nop 1
	v_add_f32_dpp v82, v82, v82 quad_perm:[1,0,3,2] row_mask:0xf bank_mask:0xf
	s_waitcnt lgkmcnt(1)
	s_waitcnt lgkmcnt(0)
	s_nop 1
	v_add_f32_dpp v80, v80, v80 quad_perm:[2,3,0,1] row_mask:0xf bank_mask:0xf
	s_nop 1
	v_add_f32_dpp v82, v82, v82 quad_perm:[2,3,0,1] row_mask:0xf bank_mask:0xf
	s_waitcnt lgkmcnt(1)
	s_waitcnt lgkmcnt(0)
	s_nop 1
	v_add_f32_dpp v80, v80, v80 row_half_mirror row_mask:0xf bank_mask:0xf
	s_nop 1
	v_add_f32_dpp v82, v82, v82 row_half_mirror row_mask:0xf bank_mask:0xf
	s_waitcnt lgkmcnt(1)
	s_waitcnt lgkmcnt(0)
	s_nop 1
	v_add_f32_dpp v80, v80, v80 row_mirror row_mask:0xf bank_mask:0xf
	s_nop 1
	v_add_f32_dpp v82, v82, v82 row_mirror row_mask:0xf bank_mask:0xf
	s_waitcnt lgkmcnt(1)
	s_waitcnt lgkmcnt(0)
	v_mov_b32_e32 v84, v80
	s_nop 1
	v_permlane16_swap_b32_e32 v84, v80
	v_mov_b32_e32 v85, v82
	s_nop 1
	v_permlane16_swap_b32_e32 v85, v82
	s_waitcnt lgkmcnt(1)
	v_add_f32_e32 v80, v80, v84
	s_waitcnt lgkmcnt(0)
	v_add_f32_e32 v82, v82, v85
	v_mov_b32_e32 v84, v80
	s_nop 1
	v_permlane32_swap_b32_e32 v84, v80
	v_mov_b32_e32 v85, v82
	s_nop 1
	v_permlane32_swap_b32_e32 v85, v82
	s_waitcnt lgkmcnt(1)
	v_add_f32_e32 v80, v80, v84
	s_waitcnt lgkmcnt(0)
	v_add_f32_e32 v82, v82, v85
	v_fmamk_f32 v80, v80, 0x3a800000, v86
	v_fmamk_f32 v82, v82, 0x3a800000, v86
	v_rsq_f32_e32 v80, v80
	v_rsq_f32_e32 v82, v82
	s_nop 0
	v_mul_f32_e32 v48, v48, v80
	v_mul_f32_e32 v64, v64, v82
	v_mul_f32_e32 v49, v49, v80
	v_mul_f32_e32 v65, v65, v82
	v_mul_f32_e32 v50, v50, v80
	v_mul_f32_e32 v66, v66, v82
	v_mul_f32_e32 v51, v51, v80
	v_mul_f32_e32 v67, v67, v82
	v_mul_f32_e32 v52, v52, v80
	v_mul_f32_e32 v68, v68, v82
	v_mul_f32_e32 v53, v53, v80
	v_mul_f32_e32 v69, v69, v82
	v_mul_f32_e32 v54, v54, v80
	v_mul_f32_e32 v70, v70, v82
	v_mul_f32_e32 v55, v55, v80
	v_mul_f32_e32 v71, v71, v82
	v_mul_f32_e32 v56, v56, v80
	v_mul_f32_e32 v72, v72, v82
	v_mul_f32_e32 v57, v57, v80
	v_mul_f32_e32 v73, v73, v82
	v_mul_f32_e32 v58, v58, v80
	v_mul_f32_e32 v74, v74, v82
	v_mul_f32_e32 v59, v59, v80
	v_mul_f32_e32 v75, v75, v82
	v_mul_f32_e32 v60, v60, v80
	v_mul_f32_e32 v76, v76, v82
	v_mul_f32_e32 v61, v61, v80
	v_mul_f32_e32 v77, v77, v82
	v_mul_f32_e32 v62, v62, v80
	v_mul_f32_e32 v78, v78, v82
	v_mul_f32_e32 v63, v63, v80
	v_mul_f32_e32 v79, v79, v82
	v_mul_f32_e32 v48, v48, v100
	v_mul_f32_e32 v64, v64, v100
	v_mul_f32_e32 v49, v49, v101
	v_mul_f32_e32 v65, v65, v101
	v_mul_f32_e32 v50, v50, v102
	v_mul_f32_e32 v66, v66, v102
	v_mul_f32_e32 v51, v51, v103
	v_mul_f32_e32 v67, v67, v103
	v_mul_f32_e32 v52, v52, v104
	v_mul_f32_e32 v68, v68, v104
	v_mul_f32_e32 v53, v53, v105
	v_mul_f32_e32 v69, v69, v105
	v_mul_f32_e32 v54, v54, v106
	v_mul_f32_e32 v70, v70, v106
	v_mul_f32_e32 v55, v55, v107
	v_mul_f32_e32 v71, v71, v107
	v_mul_f32_e32 v56, v56, v108
	v_mul_f32_e32 v72, v72, v108
	v_mul_f32_e32 v57, v57, v109
	v_mul_f32_e32 v73, v73, v109
	v_mul_f32_e32 v58, v58, v110
	v_mul_f32_e32 v74, v74, v110
	v_mul_f32_e32 v59, v59, v111
	v_mul_f32_e32 v75, v75, v111
	v_mul_f32_e32 v60, v60, v112
	v_mul_f32_e32 v76, v76, v112
	v_mul_f32_e32 v61, v61, v113
	v_mul_f32_e32 v77, v77, v113
	v_mul_f32_e32 v62, v62, v114
	v_mul_f32_e32 v78, v78, v114
	v_mul_f32_e32 v63, v63, v115
	v_mul_f32_e32 v79, v79, v115
	global_store_dwordx4 v2, v[48:51], s[14:15]
	global_store_dwordx4 v2, v[52:55], s[14:15] offset:1024
	global_store_dwordx4 v2, v[56:59], s[14:15] offset:2048
	global_store_dwordx4 v2, v[60:63], s[14:15] offset:3072
	global_store_dwordx4 v2, v[64:67], s[16:17]
	global_store_dwordx4 v2, v[68:71], s[16:17] offset:1024
	global_store_dwordx4 v2, v[72:75], s[16:17] offset:2048
	global_store_dwordx4 v2, v[76:79], s[16:17] offset:3072
	s_cmp_lg_u32 s18, 0
	s_cbranch_scc0 .LBB0_1347
	s_waitcnt vmcnt(8)
	s_branch .Lp12_loop
